# baseline (speedup 1.0000x reference)
; __device__ __forceinline__ int tid_fresh() { int t = (int)threadIdx.x; asm volatile("" : "+v"(t)); return t; }
; __device__ __forceinline__ unsigned cvt_pk_bf16(float lo, float hi) { unsigned r; asm volatile("v_cvt_pk_bf16_f32 %0, %1, %2" : "=v"(r) : "v"(lo), "v"(hi)); return r; }
; __device__ __forceinline__ void norm_phase(const float* src_l, const float* src_c, int nrows, const float* modl, int shoff, int scoff, bf16_t* xl) {
;     const int lane = tid_fresh() & 63, gw = blockIdx.x * 8 + (tid_fresh() >> 6), NGW = gridDim.x * 8;
;     for (int r = gw; r < nrows; r += NGW) {
;         const bool lat = r < MLAT; const int cond = lat ? (r >> 13) : 8;
;         const float* xr = lat ? src_l + (size_t)r * DM : src_c + (size_t)(r - MLAT) * DM;
;         const float* mp = modl + cond * 6144;
;         f32x4 v[4]; float s = 0.f;
; #pragma unroll
;         for (int j = 0; j < 4; ++j) { v[j] = *(const f32x4*)(xr + 4 * lane + 256 * j); s += v[j][0] * v[j][0] + v[j][1] * v[j][1] + v[j][2] * v[j][2] + v[j][3] * v[j][3]; }
;         const float rstd = rsqrtf(wave_sum(s) * (1.0f / DM) + EPS);
; #pragma unroll
;         for (int j = 0; j < 4; ++j) { const int col = 4 * lane + 256 * j; const f32x4 sc = *(const f32x4*)(mp + scoff + col), sh = *(const f32x4*)(mp + shoff + col);
;             const f32x4 o = v[j] * rstd * (sc + 1.0f) + sh; u32x2 w; w.x = cvt_pk_bf16(o[0], o[1]); w.y = cvt_pk_bf16(o[2], o[3]);
;             *(u32x2*)(xl + (size_t)r * DM + col) = w; }
;     }
; }
.LBB0_56:
	s_or_b64 exec, exec, s[12:13]
	v_lshl_add_u64 v[18:19], v[18:19], 0, v[8:9]
	global_load_dwordx4 v[28:31], v[18:19], off nt
	global_load_dwordx4 v[32:35], v[18:19], off offset:1024 nt
	global_load_dwordx4 v[36:39], v[18:19], off offset:2048 nt
	global_load_dwordx4 v[40:43], v[18:19], off offset:3072 nt
	v_min_i32_e32 v2, 0x10000, v0
	v_ashrrev_i32_e32 v2, 13, v2
	v_mul_i32_i24_e32 v18, 0x1800, v2
	v_ashrrev_i32_e32 v19, 31, v18
	v_lshl_add_u64 v[18:19], v[18:19], 2, s[54:55]
	v_lshl_add_u64 v[52:53], v[18:19], 0, s[10:11]
	v_lshl_add_u64 v[44:45], v[52:53], 0, v[8:9]
	global_load_dwordx4 v[44:47], v[44:45], off
	v_lshl_add_u64 v[54:55], v[18:19], 0, v[8:9]
	global_load_dwordx4 v[48:51], v[54:55], off
	v_lshl_add_u64 v[70:71], v[52:53], 0, v[10:11]
	global_load_dwordx4 v[72:75], v[70:71], off
	global_load_dwordx4 v[76:79], v[54:55], off offset:1024
	v_lshl_add_u64 v[70:71], v[52:53], 0, v[12:13]
	global_load_dwordx4 v[80:83], v[70:71], off
	global_load_dwordx4 v[84:87], v[54:55], off offset:2048
	v_lshl_add_u64 v[70:71], v[52:53], 0, v[14:15]
	global_load_dwordx4 v[88:91], v[70:71], off
	global_load_dwordx4 v[92:95], v[54:55], off offset:3072
	v_lshlrev_b64 v[16:17], 11, v[16:17]
	v_lshl_add_u64 v[0:1], v[0:1], 0, s[78:79]
	v_min_i32_e32 v96, 0xffff, v0
	v_and_b32_e32 v97, 31, v204
	v_lshlrev_b32_e32 v96, 12, v96
	v_lshl_add_u32 v96, v97, 7, v96
	global_load_dword v98, v96, s[0:1]
	v_lshl_add_u64 v[6:7], v[6:7], 0, s[6:7]
	s_waitcnt vmcnt(12)
	v_mov_b32_e32 v56, v29
	s_waitcnt vmcnt(11)
	v_mov_b32_e32 v57, v33
	v_mov_b32_e32 v18, v28
	v_mov_b32_e32 v19, v32
	s_waitcnt vmcnt(10)
	v_mov_b32_e32 v64, v37
	s_waitcnt vmcnt(9)
	v_mov_b32_e32 v65, v41
	v_pk_mul_f32 v[56:57], v[56:57], v[56:57]
	v_mov_b32_e32 v58, v30
	v_mov_b32_e32 v59, v34
	v_mov_b32_e32 v62, v36
	v_mov_b32_e32 v63, v40
	v_pk_mul_f32 v[64:65], v[64:65], v[64:65]
	v_pk_fma_f32 v[18:19], v[18:19], v[18:19], v[56:57]
	v_mov_b32_e32 v60, v31
	v_mov_b32_e32 v61, v35
	v_mov_b32_e32 v66, v38
	v_mov_b32_e32 v67, v42
	v_pk_fma_f32 v[56:57], v[62:63], v[62:63], v[64:65]
	v_pk_fma_f32 v[18:19], v[58:59], v[58:59], v[18:19]
	v_mov_b32_e32 v68, v39
	v_mov_b32_e32 v69, v43
	v_pk_fma_f32 v[56:57], v[66:67], v[66:67], v[56:57]
	v_pk_fma_f32 v[18:19], v[60:61], v[60:61], v[18:19]
	v_pk_fma_f32 v[56:57], v[68:69], v[68:69], v[56:57]
	v_add_f32_e32 v2, v18, v19
	v_add_f32_e32 v2, v2, v56
	v_add_f32_e32 v2, v2, v57
	ds_bpermute_b32 v18, v20, v2
	v_lshl_add_u64 v[56:57], v[4:5], 0, v[16:17]
	s_waitcnt vmcnt(8)
	v_pk_add_f32 v[44:45], v[44:45], 1.0 op_sel_hi:[1,0]
	s_waitcnt lgkmcnt(0)
	v_add_f32_e32 v2, v2, v18
	ds_bpermute_b32 v18, v21, v2
	s_waitcnt lgkmcnt(0)
	v_add_f32_e32 v2, v2, v18
	ds_bpermute_b32 v18, v22, v2
	s_waitcnt lgkmcnt(0)
	v_add_f32_e32 v2, v2, v18
	ds_bpermute_b32 v18, v23, v2
	s_waitcnt lgkmcnt(0)
	v_add_f32_e32 v2, v2, v18
	ds_bpermute_b32 v18, v24, v2
	s_waitcnt lgkmcnt(0)
	v_add_f32_e32 v2, v2, v18
	ds_bpermute_b32 v18, v25, v2
	s_waitcnt lgkmcnt(0)
	v_add_f32_e32 v2, v2, v18
	v_fmamk_f32 v2, v2, 0x3a800000, v26
	v_mul_f32_e32 v16, 0x4b800000, v2
	v_cmp_gt_f32_e32 vcc, s15, v2
	v_pk_add_f32 v[18:19], v[46:47], 1.0 op_sel_hi:[1,0]
	s_nop 0
	v_cndmask_b32_e32 v2, v2, v16, vcc
	v_rsq_f32_e32 v2, v2
	v_lshl_add_u64 v[16:17], v[52:53], 0, v[10:11]
	v_mul_f32_e32 v27, 0x45800000, v2
	v_cndmask_b32_e32 v2, v2, v27, vcc
	v_pk_mul_f32 v[28:29], v[28:29], v[2:3] op_sel_hi:[1,0]
	v_pk_mul_f32 v[30:31], v[30:31], v[2:3] op_sel_hi:[1,0]
	s_waitcnt vmcnt(7)
	v_pk_fma_f32 v[28:29], v[44:45], v[28:29], v[48:49]
	v_pk_fma_f32 v[18:19], v[18:19], v[30:31], v[50:51]
	v_cvt_pk_bf16_f32 v28, v28, v29
	v_pk_mul_f32 v[32:33], v[32:33], v[2:3] op_sel_hi:[1,0]
	v_cvt_pk_bf16_f32 v29, v18, v19
	global_store_dwordx2 v[56:57], v[28:29], off
	v_pk_mul_f32 v[34:35], v[34:35], v[2:3] op_sel_hi:[1,0]
	v_lshl_add_u64 v[44:45], v[52:53], 0, v[12:13]
	v_cmp_lt_i32_e32 vcc, s26, v0
	s_or_b64 s[8:9], vcc, s[8:9]
	s_waitcnt vmcnt(7)
	v_pk_add_f32 v[16:17], v[72:73], 1.0 op_sel_hi:[1,0]
	v_pk_add_f32 v[18:19], v[74:75], 1.0 op_sel_hi:[1,0]
	s_waitcnt vmcnt(6)
	v_pk_fma_f32 v[16:17], v[16:17], v[32:33], v[76:77]
	v_pk_fma_f32 v[18:19], v[18:19], v[34:35], v[78:79]
	v_cvt_pk_bf16_f32 v16, v16, v17
	v_pk_mul_f32 v[34:35], v[36:37], v[2:3] op_sel_hi:[1,0]
	v_cvt_pk_bf16_f32 v17, v18, v19
	global_store_dwordx2 v[56:57], v[16:17], off offset:512
	v_pk_mul_f32 v[36:37], v[38:39], v[2:3] op_sel_hi:[1,0]
	v_lshl_add_u64 v[32:33], v[52:53], 0, v[14:15]
	s_waitcnt vmcnt(6)
	v_pk_add_f32 v[16:17], v[80:81], 1.0 op_sel_hi:[1,0]
	v_pk_add_f32 v[18:19], v[82:83], 1.0 op_sel_hi:[1,0]
	s_waitcnt vmcnt(5)
	v_pk_fma_f32 v[16:17], v[16:17], v[34:35], v[84:85]
	v_pk_fma_f32 v[18:19], v[18:19], v[36:37], v[86:87]
	v_cvt_pk_bf16_f32 v16, v16, v17
	v_pk_mul_f32 v[34:35], v[42:43], v[2:3] op_sel_hi:[1,0]
	v_cvt_pk_bf16_f32 v17, v18, v19
	global_store_dwordx2 v[56:57], v[16:17], off offset:1024
	v_pk_mul_f32 v[32:33], v[40:41], v[2:3] op_sel_hi:[1,0]
	s_waitcnt vmcnt(5)
	v_pk_add_f32 v[16:17], v[88:89], 1.0 op_sel_hi:[1,0]
	v_pk_add_f32 v[18:19], v[90:91], 1.0 op_sel_hi:[1,0]
	s_waitcnt vmcnt(4)
	v_pk_fma_f32 v[16:17], v[32:33], v[16:17], v[92:93]
	v_pk_fma_f32 v[18:19], v[34:35], v[18:19], v[94:95]
	v_cvt_pk_bf16_f32 v16, v16, v17
	s_nop 0
	v_cvt_pk_bf16_f32 v17, v18, v19
	global_store_dwordx2 v[56:57], v[16:17], off offset:1536
	s_andn2_b64 exec, exec, s[8:9]
	s_cbranch_execz .LBB0_59
